# baseline (speedup 1.0000x reference)
; #define LAS __attribute__((address_space(3)))
; #define GAS __attribute__((address_space(1)))
; #define ATT_KRD(KOFF, DLO, DHI) do { _Pragma("unroll") for (int d0 = (DLO); d0 < (DHI); ++d0) { kf[2 * d0] = *(const LAS bf16x8*)(lds + (KOFF) + kr + 2 * d0 * KCH); kf[2 * d0 + 1] = *(const LAS bf16x8*)(lds + (KOFF) + kr + 2 * d0 * KCH + 512); } } while (0)
; __device__ __forceinline__ void attn_unit(LAS unsigned char* lds, bf16_t* Qm, const bf16_t* __restrict__ Kb, const bf16_t* __restrict__ Vt,
;                                           int b, int h, int qb, int lgS, float lam, float oscale, const float* __restrict__ subg, float* stash) {
;     ...
;         const bf16_t* qp = Qm + (size_t)(tok0 + r32) * MIXW + (2 * h + c) * 64 + hi * 8;
;         bf16x8 qf[4];
; #pragma unroll
;         for (int d0 = 0; d0 < 4; ++d0) qf[d0] = *(const GAS bf16x8*)(qp + d0 * 16);
; #pragma unroll
;         for (int i = 0; i < 4; ++i)
; #pragma unroll
;             for (int r = 0; r < 16; ++r) o[i][r] = 0.f;
;         float mhat, lrun;
;         f32x16 negm;
; #pragma unroll
;         for (int r = 0; r < 16; ++r) negm[r] = 0.f;
;         const bf16_t* kg = Kb + (size_t)((b << lgS) + (tid >> 3)) * 512 + (2 * h + c) * 64 + (tid & 7) * 8;
;         const bf16_t* vg0 = Vt + ((size_t)(b * 512 + h * 128 + (tid >> 3)) << lgS) + (tid & 7) * 8;
;         const bf16_t* vg1 = vg0 + ((size_t)64 << lgS);
;         u32x4 kreg, vreg0, vreg1;
;         {
;             kreg = *(const GAS u32x4*)kg; vreg0 = *(const GAS u32x4*)vg0; vreg1 = *(const GAS u32x4*)vg1;
;             const u32x4 k1 = *(const GAS u32x4*)(kg + (size_t)64 * 512), k2 = *(const GAS u32x4*)(kg + (size_t)2 * 64 * 512), v10 = *(const GAS u32x4*)(vg0 + 64), v11 = *(const GAS u32x4*)(vg1 + 64);
;             *(LAS u32x4*)(lds + kw) = kreg; *(LAS u32x4*)(lds + vw0) = vreg0; *(LAS u32x4*)(lds + vw1) = vreg1;
;             *(LAS u32x4*)(lds + KBUF + kw) = k1; *(LAS u32x4*)(lds + VBUF + vw0) = v10; *(LAS u32x4*)(lds + VBUF + vw1) = v11;
;             *(LAS u32x4*)(lds + 2 * KBUF + kw) = k2;
;             kreg = *(const GAS u32x4*)(kg + (size_t)3 * 64 * 512); vreg0 = *(const GAS u32x4*)(vg0 + 2 * 64); vreg1 = *(const GAS u32x4*)(vg1 + 2 * 64);
;         }
;         __syncthreads();
;         u32x4 pk[4]; bf16x8 kf[8]; bf16x8 vfa[4], vfb[4];
;         {
;             f32x16 p0, p1;
;             ATT_KRD(0, 0, 4);
;             ATT_QK(p0, p1);
.LBB0_334:
	s_or_b32 s90, s25, s5
	s_lshl_b64 s[28:29], s[90:91], 1
	v_lshl_add_u64 v[12:13], v[228:229], 0, s[28:29]
	v_add_co_u32_e32 v4, vcc, 0x10000, v12
	v_lshl_add_u64 v[14:15], v[226:227], 0, s[28:29]
	s_nop 0
	v_addc_co_u32_e32 v5, vcc, 0, v13, vcc
	global_load_dwordx4 v[0:3], v[12:13], off
	s_nop 0
	global_load_dwordx4 v[4:7], v[4:5], off
	v_add_co_u32_e32 v8, vcc, 0x20000, v12
	v_add_u32_e32 v16, 0, v234
	s_nop 0
	v_addc_co_u32_e32 v9, vcc, 0, v13, vcc
	global_load_dwordx4 v[8:11], v[8:9], off
	s_nop 0
	global_load_dwordx4 v[136:139], v[14:15], off
	global_load_dwordx4 v[140:143], v[14:15], off offset:32
	global_load_dwordx4 v[144:147], v[14:15], off offset:64
	global_load_dwordx4 v[148:151], v[14:15], off offset:96
	v_add_co_u32_e32 v12, vcc, 0x30000, v12
	s_waitcnt vmcnt(8)
	v_mov_b64_e32 v[170:171], v[130:131]
	v_addc_co_u32_e32 v13, vcc, 0, v13, vcc
	global_load_dwordx4 v[152:155], v[12:13], off
	s_waitcnt vmcnt(8)
	v_mov_b64_e32 v[178:179], v[134:135]
	v_lshl_add_u64 v[238:239], v[236:237], 0, s[28:29]
	s_mov_b32 s56, 0x9000
	s_movk_i32 s50, 0x2100
	s_movk_i32 s29, 0x4200
	s_movk_i32 s25, 0x4800
	s_movk_i32 s90, 0xc0
	v_mov_b64_e32 v[168:169], v[128:129]
	v_mov_b64_e32 v[176:177], v[132:133]
	s_mov_b32 s28, 0
	s_mov_b32 s57, 0
	s_mov_b32 s60, 0
	s_waitcnt vmcnt(7)
	ds_write_b128 v248, v[0:3]
	ds_write_b128 v16, v[112:115] offset:25344
	ds_write_b128 v16, v[116:119] offset:34560
	s_waitcnt vmcnt(6)
	ds_write_b128 v248, v[4:7] offset:8448
	ds_write_b128 v16, v[120:123] offset:43776
	ds_write_b128 v16, v[124:127] offset:52992
	s_waitcnt vmcnt(5)
	ds_write_b128 v248, v[8:11] offset:16896
	s_waitcnt lgkmcnt(0)
	s_barrier
	ds_read_b128 v[0:3], v235
	ds_read_b128 v[18:21], v235 offset:512
	s_waitcnt vmcnt(4) lgkmcnt(1)
	v_mfma_f32_32x32x16_bf16 v[2:17], v[0:3], v[136:139], 0
	ds_read_b128 v[34:37], v235 offset:2112
	ds_read_b128 v[38:41], v235 offset:2624
	v_mov_b32_e32 v0, 0
	v_mov_b32_e32 v51, v0
	v_mov_b32_e32 v52, v0
	v_mov_b32_e32 v53, v0
	v_mov_b32_e32 v54, v0
	v_mov_b32_e32 v55, v0
	s_waitcnt lgkmcnt(2)
	v_mfma_f32_32x32x16_bf16 v[18:33], v[18:21], v[136:139], 0
	v_mov_b32_e32 v56, v0
	v_mov_b32_e32 v57, v0
	v_mov_b32_e32 v58, v0
	v_mov_b32_e32 v59, v0
	v_mov_b32_e32 v60, v0
	v_mov_b32_e32 v61, v0
	v_mov_b32_e32 v62, v0
	s_waitcnt vmcnt(3) lgkmcnt(1)
	v_mfma_f32_32x32x16_bf16 v[2:17], v[34:37], v[140:143], v[2:17]
	v_mov_b32_e32 v63, v0
	s_waitcnt lgkmcnt(0)
	v_mfma_f32_32x32x16_bf16 v[18:33], v[38:41], v[140:143], v[18:33]
	ds_read_b128 v[34:37], v235 offset:4224
	ds_read_b128 v[38:41], v235 offset:4736
	s_waitcnt vmcnt(2) lgkmcnt(1)
	v_mfma_f32_32x32x16_bf16 v[2:17], v[34:37], v[144:147], v[2:17]
	ds_read_b128 v[34:37], v235 offset:6336
	s_waitcnt lgkmcnt(1)
	v_mfma_f32_32x32x16_bf16 v[18:33], v[38:41], v[144:147], v[18:33]
	ds_read_b128 v[38:41], v235 offset:6848
	ds_read_b128 v[156:159], v235 offset:8448
	ds_read_b128 v[160:163], v235 offset:8960
	ds_read_b128 v[204:207], v235 offset:10560
	ds_read_b128 v[208:211], v235 offset:11072
	ds_read_b128 v[212:215], v235 offset:12672
	ds_read_b128 v[216:219], v235 offset:13184
	ds_read_b128 v[222:225], v235 offset:14784
	ds_read_b128 v[240:243], v235 offset:15296
	ds_read_b128 v[196:199], v220 offset:25344
	ds_read_b128 v[192:195], v220 offset:29952
	ds_read_b128 v[188:191], v220 offset:34560
	ds_read_b128 v[184:187], v220 offset:39168
	s_waitcnt lgkmcnt(0)
	s_barrier
; __device__ __forceinline__ void attn_unit(LAS unsigned char* lds, bf16_t* Qm, const bf16_t* __restrict__ Kb, const bf16_t* __restrict__ Vt,
;                                           int b, int h, int qb, int lgS, float lam, float oscale, const float* __restrict__ subg, float* stash) {
;     ...
;             float mx;
;             {
;                 float a_ = ATT_MX3(p0[0], p0[1], p1[0]), b_ = ATT_MX3(p0[2], p0[3], p1[1]); a_ = ATT_MX3(a_, p1[2], p1[3]);
; #pragma unroll
;                 for (int r = 4; r < 16; r += 4) { a_ = ATT_MX3(a_, p0[r], p0[r + 1]); b_ = ATT_MX3(b_, p0[r + 2], p0[r + 3]); a_ = ATT_MX3(a_, p1[r], p1[r + 1]); b_ = ATT_MX3(b_, p1[r + 2], p1[r + 3]); }
;                 const float m_ = __builtin_fmaxf(a_, b_);
;                 auto rr_ = __builtin_amdgcn_permlane32_swap(__float_as_uint(m_), __float_as_uint(m_), false, false);
;                 mx = __builtin_fmaxf(__uint_as_float(rr_[0]), __uint_as_float(rr_[1]));
;             }
;             mhat = mx;
; #pragma unroll
;             for (int r = 0; r < 16; ++r) negm[r] = -mx;
;             float sum = 0.f;
; #pragma unroll
;             for (int r = 0; r < 16; ++r) { p0[r] = __builtin_amdgcn_exp2f(p0[r] - mx); p1[r] = __builtin_amdgcn_exp2f(p1[r] - mx); sum += p0[r] + p1[r]; }
;             lrun = sum;
; #pragma unroll
;             for (int j = 0; j < 8; ++j) { pk[j >> 2][j & 3] = cvtpk_s(p0[2 * j], p0[2 * j + 1]); pk[2 + (j >> 2)][j & 3] = cvtpk_s(p1[2 * j], p1[2 * j + 1]); }
;             ATT_KRD(KBUF, 0, 1);
; #pragma unroll
;             for (int b2 = 0; b2 < 4; ++b2) vfa[b2] = *(const LAS bf16x8*)(lds + vr + b2 * 32 * VP);
;         }
;         __syncthreads();
;         int vs0 = 0, vs1 = VBUF, vs2 = 2 * VBUF;
;         int kq0 = 0, kq1 = KBUF, kq2 = 2 * KBUF;
; #pragma unroll 1
;         for (int t = 0; t < NT - 1; ++t) {
;             if (t + 3 < NT) *(LAS u32x4*)(lds + kq0 + kw) = kreg;
;             if (t + 2 < NT) { *(LAS u32x4*)(lds + vs2 + vw0) = vreg0; *(LAS u32x4*)(lds + vs2 + vw1) = vreg1; }
;             if (t + 4 < NT) kreg = *(const GAS u32x4*)(kg + (size_t)(t + 4) * 64 * 512);
;             if (t + 3 < NT) { vreg0 = *(const GAS u32x4*)(vg0 + (t + 3) * 64); vreg1 = *(const GAS u32x4*)(vg1 + (t + 3) * 64); }
;             f32x16 p0, p1;
;             ATT_KRD(kq1, 1, 4);
;             ATT_SB();
;             __builtin_amdgcn_s_setprio(1);
;             ATT_QK(p0, p1);
	s_waitcnt vmcnt(1)
	v_mfma_f32_32x32x16_bf16 v[2:17], v[34:37], v[148:151], v[2:17]
	v_mfma_f32_32x32x16_bf16 v[18:33], v[38:41], v[148:151], v[18:33]
	s_nop 10
	v_max_f32_e32 v1, v3, v3
	v_max_f32_e32 v34, v2, v2
	v_max_f32_e32 v1, v34, v1
	v_max3_f32 v35, v4, v5, v19
	v_max3_f32 v1, v1, v18, v20
	v_max3_f32 v34, v35, v8, v9
	v_max3_f32 v1, v1, v21, v6
	v_max3_f32 v34, v34, v24, v25
	v_max3_f32 v1, v1, v7, v22
	v_max3_f32 v34, v34, v12, v13
	v_max3_f32 v1, v1, v23, v10
	v_max3_f32 v34, v34, v28, v29
	v_max3_f32 v1, v1, v11, v26
	v_max3_f32 v34, v34, v16, v17
	v_max3_f32 v1, v1, v27, v14
	v_max3_f32 v34, v34, v32, v33
	v_max3_f32 v1, v1, v15, v30
	v_max3_f32 v1, v1, v31, v34
	v_mov_b32_e32 v34, v1
	s_nop 1
	v_permlane32_swap_b32_e32 v1, v34
	v_max_f32_e32 v34, v34, v34
	v_max_f32_e32 v1, v1, v1
	v_max_f32_e32 v250, v1, v34
	v_sub_f32_e32 v1, v26, v250
	v_sub_f32_e32 v26, v27, v250
	v_sub_f32_e32 v27, v28, v250
	v_sub_f32_e32 v28, v29, v250
	v_sub_f32_e32 v29, v30, v250
	v_sub_f32_e32 v30, v31, v250
	v_sub_f32_e32 v31, v32, v250
	v_sub_f32_e32 v41, v18, v250
	v_sub_f32_e32 v42, v19, v250
	v_sub_f32_e32 v47, v2, v250
	v_sub_f32_e32 v32, v33, v250
	v_sub_f32_e32 v36, v13, v250
	v_sub_f32_e32 v48, v3, v250
	v_sub_f32_e32 v49, v4, v250
	v_exp_f32_e32 v3, v1
	v_exp_f32_e32 v4, v28
	v_exp_f32_e32 v13, v31
	v_exp_f32_e32 v1, v41
	v_exp_f32_e32 v28, v42
	v_exp_f32_e32 v31, v47
	v_sub_f32_e32 v33, v10, v250
	v_sub_f32_e32 v35, v12, v250
	v_sub_f32_e32 v43, v20, v250
	v_exp_f32_e32 v12, v32
	v_exp_f32_e32 v32, v48
	v_sub_f32_e32 v34, v11, v250
	v_sub_f32_e32 v38, v15, v250
	v_sub_f32_e32 v44, v21, v250
	v_sub_f32_e32 v50, v5, v250
	v_exp_f32_e32 v11, v29
	v_exp_f32_e32 v15, v33
	v_exp_f32_e32 v29, v43
	v_exp_f32_e32 v33, v49
	v_sub_f32_e32 v37, v14, v250
	v_sub_f32_e32 v22, v22, v250
	v_sub_f32_e32 v45, v23, v250
	v_exp_f32_e32 v10, v30
	v_exp_f32_e32 v14, v34
	v_exp_f32_e32 v30, v44
	v_exp_f32_e32 v34, v50
	v_sub_f32_e32 v6, v6, v250
	v_exp_f32_e32 v5, v27
	v_exp_f32_e32 v23, v22
	v_exp_f32_e32 v22, v45
	v_cvt_pk_bf16_f32 v172, v1, v28
	v_exp_f32_e32 v27, v6
	v_sub_f32_e32 v6, v7, v250
	v_add_f32_e32 v1, v1, v31
	v_exp_f32_e32 v2, v26
	v_exp_f32_e32 v26, v6
	v_sub_f32_e32 v6, v8, v250
	v_add_f32_e32 v1, 0, v1
	v_add_f32_e32 v8, v28, v32
	v_add_f32_e32 v1, v8, v1
	v_add_f32_e32 v8, v29, v33
	v_sub_f32_e32 v24, v24, v250
	v_sub_f32_e32 v46, v25, v250
	v_add_f32_e32 v1, v8, v1
	v_add_f32_e32 v8, v30, v34
	v_exp_f32_e32 v25, v24
	v_exp_f32_e32 v24, v46
	v_exp_f32_e32 v7, v6
	v_sub_f32_e32 v6, v9, v250
	v_add_f32_e32 v1, v8, v1
	v_pk_mov_b32 v[8:9], v[22:23], v[22:23] op_sel:[1,0]
	v_exp_f32_e32 v6, v6
	v_cvt_pk_bf16_f32 v174, v8, v9
	v_pk_mov_b32 v[8:9], v[26:27], v[26:27] op_sel:[1,0]
	v_sub_f32_e32 v39, v16, v250
	v_cvt_pk_bf16_f32 v202, v8, v9
	v_pk_add_f32 v[8:9], v[22:23], v[26:27]
	v_sub_f32_e32 v40, v17, v250
	v_add_f32_e32 v1, v9, v1
	v_add_f32_e32 v1, v8, v1
	v_pk_mov_b32 v[8:9], v[24:25], v[24:25] op_sel:[1,0]
	v_exp_f32_e32 v17, v35
	v_cvt_pk_bf16_f32 v175, v8, v9
	v_pk_mov_b32 v[8:9], v[6:7], v[6:7] op_sel:[1,0]
	v_pk_add_f32 v[6:7], v[24:25], v[6:7]
	v_exp_f32_e32 v16, v36
	v_add_f32_e32 v1, v7, v1
	v_add_f32_e32 v1, v6, v1
	v_pk_mov_b32 v[6:7], v[2:3], v[2:3] op_sel:[1,0]
	v_pk_add_f32 v[2:3], v[2:3], v[14:15]
	v_exp_f32_e32 v19, v37
	v_add_f32_e32 v1, v3, v1
	v_add_f32_e32 v1, v2, v1
	v_pk_mov_b32 v[2:3], v[4:5], v[4:5] op_sel:[1,0]
	v_exp_f32_e32 v18, v38
	v_cvt_pk_bf16_f32 v165, v2, v3
	v_pk_mov_b32 v[2:3], v[16:17], v[16:17] op_sel:[1,0]
	v_exp_f32_e32 v21, v39
	v_cvt_pk_bf16_f32 v181, v2, v3
	v_pk_add_f32 v[2:3], v[4:5], v[16:17]
	v_exp_f32_e32 v20, v40
	v_add_f32_e32 v1, v3, v1
	v_add_f32_e32 v1, v2, v1
	v_pk_mov_b32 v[2:3], v[10:11], v[10:11] op_sel:[1,0]
	v_xor_b32_e32 v64, 0x80000000, v250
	v_cvt_pk_bf16_f32 v166, v2, v3
	v_pk_mov_b32 v[2:3], v[18:19], v[18:19] op_sel:[1,0]
	v_cvt_pk_bf16_f32 v164, v6, v7
	v_cvt_pk_bf16_f32 v182, v2, v3
	v_pk_add_f32 v[2:3], v[10:11], v[18:19]
	v_pk_mov_b32 v[6:7], v[14:15], v[14:15] op_sel:[1,0]
	v_add_f32_e32 v1, v3, v1
	v_add_f32_e32 v1, v2, v1
	v_pk_mov_b32 v[2:3], v[12:13], v[12:13] op_sel:[1,0]
	v_cvt_pk_bf16_f32 v173, v29, v30
	v_cvt_pk_bf16_f32 v167, v2, v3
	v_pk_mov_b32 v[2:3], v[20:21], v[20:21] op_sel:[1,0]
	v_cvt_pk_bf16_f32 v200, v31, v32
	v_cvt_pk_bf16_f32 v183, v2, v3
	v_pk_add_f32 v[2:3], v[12:13], v[20:21]
	v_cvt_pk_bf16_f32 v201, v33, v34
	v_add_f32_e32 v1, v3, v1
	v_cvt_pk_bf16_f32 v203, v8, v9
	v_cvt_pk_bf16_f32 v180, v6, v7
	v_add_f32_e32 v249, v2, v1
	v_mov_b32_e32 v1, v0
	v_mov_b32_e32 v2, v0
	v_mov_b32_e32 v3, v0
	v_mov_b32_e32 v4, v0
	v_mov_b32_e32 v5, v0
	v_mov_b32_e32 v6, v0
	v_mov_b32_e32 v7, v0
	v_mov_b32_e32 v8, v0
	v_mov_b32_e32 v9, v0
	v_mov_b32_e32 v10, v0
	v_mov_b32_e32 v11, v0
	v_mov_b32_e32 v12, v0
	v_mov_b32_e32 v13, v0
	v_mov_b32_e32 v14, v0
	v_mov_b32_e32 v15, v0
	v_mov_b32_e32 v48, v0
	v_mov_b32_e32 v49, v0
	v_mov_b32_e32 v50, v0
	v_mov_b32_e32 v32, v0
	v_mov_b32_e32 v33, v0
	v_mov_b32_e32 v34, v0
	v_mov_b32_e32 v35, v0
	v_mov_b32_e32 v36, v0
	v_mov_b32_e32 v37, v0
	v_mov_b32_e32 v38, v0
	v_mov_b32_e32 v39, v0
	v_mov_b32_e32 v40, v0
	v_mov_b32_e32 v41, v0
	v_mov_b32_e32 v42, v0
	v_mov_b32_e32 v43, v0
	v_mov_b32_e32 v44, v0
	v_mov_b32_e32 v45, v0
	v_mov_b32_e32 v46, v0
	v_mov_b32_e32 v47, v0
	v_mov_b32_e32 v16, v0
	v_mov_b32_e32 v17, v0
	v_mov_b32_e32 v18, v0
	v_mov_b32_e32 v19, v0
	v_mov_b32_e32 v20, v0
	v_mov_b32_e32 v21, v0
	v_mov_b32_e32 v22, v0
	v_mov_b32_e32 v23, v0
	v_mov_b32_e32 v24, v0
	v_mov_b32_e32 v25, v0
	v_mov_b32_e32 v26, v0
	v_mov_b32_e32 v27, v0
	v_mov_b32_e32 v28, v0
	v_mov_b32_e32 v29, v0
	v_mov_b32_e32 v30, v0
	v_mov_b32_e32 v31, v0
	v_mov_b32_e32 v65, v64
	v_mov_b32_e32 v66, v64
	v_mov_b32_e32 v67, v64
	v_mov_b32_e32 v68, v64
	v_mov_b32_e32 v69, v64
	v_mov_b32_e32 v70, v64
	v_mov_b32_e32 v71, v64
	v_mov_b32_e32 v72, v64
	v_mov_b32_e32 v73, v64
	v_mov_b32_e32 v74, v64
	v_mov_b32_e32 v75, v64
	v_mov_b32_e32 v76, v64
	v_mov_b32_e32 v77, v64
	v_mov_b32_e32 v78, v64
	v_mov_b32_e32 v79, v64
	s_cmp_lg_u32 s98, 0
	s_cbranch_scc1 .Lmy_noprio
	s_setprio 1
